# group-size division simplification extended to all streamed GEMM unit headers
# speedup vs baseline: 1.0033x; 1.0033x over previous
.LBB0_165:
	s_ashr_i32 s10, s14, 3
	s_add_i32 s10, s40, s10
	s_ashr_i32 s11, s10, 31
	s_lshr_b32 s11, s11, 27
	s_add_i32 s11, s10, s11
	s_ashr_i32 s14, s11, 5
	s_lshl_b32 s14, s14, 3
	s_andn2_b32 s11, s11, 31
	s_sub_i32 s11, s10, s11
	s_lshr_b32 s10, s11, 3
	s_and_b32 s11, s11, 7
	s_add_i32 s14, s14, s11

.LBB0_187:
	s_ashr_i32 s10, s14, 3
	s_add_i32 s10, s42, s10
	s_ashr_i32 s11, s10, 31
	s_lshr_b32 s11, s11, 27
	s_add_i32 s11, s10, s11
	s_ashr_i32 s14, s11, 5
	s_lshl_b32 s14, s14, 3
	s_andn2_b32 s11, s11, 31
	s_sub_i32 s10, s10, s11
	s_lshr_b32 s66, s10, 3
	s_and_b32 s10, s10, 7
	s_add_i32 s67, s14, s10

.LBB0_249:
	s_ashr_i32 s10, s14, 3
	s_add_i32 s10, s40, s10
	s_ashr_i32 s11, s10, 31
	s_lshr_b32 s11, s11, 28
	s_add_i32 s11, s10, s11
	s_ashr_i32 s14, s11, 4
	s_lshl_b32 s14, s14, 3
	s_and_b32 s11, s11, -16
	s_sub_i32 s11, s10, s11
	s_lshr_b32 s10, s11, 3
	s_and_b32 s11, s11, 7
	s_add_i32 s14, s14, s11

.LBB0_634:
	s_ashr_i32 s10, s14, 3
	s_add_i32 s10, s40, s10
	s_ashr_i32 s11, s10, 31
	s_lshr_b32 s11, s11, 27
	s_add_i32 s11, s10, s11
	s_ashr_i32 s14, s11, 5
	s_lshl_b32 s14, s14, 3
	s_andn2_b32 s11, s11, 31
	s_sub_i32 s10, s10, s11
	s_lshr_b32 s50, s10, 3
	s_and_b32 s10, s10, 7
	s_add_i32 s51, s14, s10
